# M2 kmax loop: next row's two loads prefetched before waiting for the current row (unrolled by two, swapped registers), over-read drained at exit
# speedup vs baseline: 1.0058x; 1.0005x over previous
; __device__ __forceinline__ float bflo(unsigned w) { return __uint_as_float(w << 16); }
; __device__ __forceinline__ float bfhi(unsigned w) { return __uint_as_float(w & 0xffff0000u); }
; __global__ void __launch_bounds__(512, 2) mega(Params p) {
;     ...
;         { float mx = 0.f;
;           for (int row = gw; row < TT; row += ngw) { const u16* kp = P + (size_t)row * PST + C_CK + lane * 16;
;               const uint4 a = *(const uint4*)kp, b2 = *(const uint4*)(kp + 8); const unsigned ww[8] = {a.x, a.y, a.z, a.w, b2.x, b2.y, b2.z, b2.w}; float ss = 0.f;
; #pragma unroll
;               for (int e = 0; e < 8; ++e) { const float x0 = bflo(ww[e]), x1 = bfhi(ww[e]); ss += x0 * x0 + x1 * x1; }
;               ss += __shfl_xor(ss, 1); ss += __shfl_xor(ss, 2); ss += __shfl_xor(ss, 4); mx = fmaxf(mx, ss); }
;           if ((lane & 7) == 0) atomicMax((unsigned*)(ws + WS_CTL) + CW_KMAX + l * 8 + (lane >> 3), __float_as_uint(mx)); }
.LBB0_634:
	s_or_b64 exec, exec, s[0:1]
	v_mov_b32_e32 v2, v170
	s_waitcnt lgkmcnt(0)
	s_barrier
	v_readlane_b32 s0, v253, 59
	v_ashrrev_i32_e32 v0, 6, v2
	v_readlane_b32 s1, v253, 60
	v_add_u32_e32 v4, s0, v0
	s_movk_i32 s0, 0x2100
	v_cmp_gt_i32_e32 vcc, s0, v4
	v_mov_b32_e32 v3, 0
	s_and_saveexec_b64 s[0:1], vcc
	s_cbranch_execz .LBB0_638
	v_cmp_lt_i32_e32 vcc, v178, v172
	v_readlane_b32 s6, v253, 59
	v_readlane_b32 s7, v253, 60
	v_cndmask_b32_e32 v1, v171, v178, vcc
	v_cmp_lt_i32_e32 vcc, v177, v172
	v_lshlrev_b32_e32 v5, 2, v1
	v_and_b32_e32 v3, 63, v2
	v_cndmask_b32_e32 v1, v171, v177, vcc
	v_cmp_lt_i32_e32 vcc, v176, v172
	v_lshlrev_b32_e32 v6, 2, v1
	v_lshlrev_b32_e32 v164, 5, v3
	v_cndmask_b32_e32 v1, v171, v176, vcc
	v_lshlrev_b32_e32 v7, 2, v1
	v_ashrrev_i32_e32 v1, 31, v0
	v_lshl_add_u64 v[0:1], s[6:7], 0, v[0:1]
	v_mad_u64_u32 v[8:9], s[6:7], v0, s93, v[164:165]
	v_readlane_b32 s6, v254, 7
	v_mad_i32_i24 v9, v1, s93, v9
	v_readlane_b32 s7, v254, 8
	v_mov_b32_e32 v3, 0
	s_mov_b64 s[34:35], 0
	v_lshl_add_u64 v[0:1], s[6:7], 0, v[8:9]
	v_readlane_b32 s6, v254, 26
	v_readlane_b32 s7, v254, 27
	global_load_dwordx4 v[8:11], v[0:1], off
	global_load_dwordx4 v[12:15], v[0:1], off offset:-16
	v_lshl_add_u64 v[0:1], v[0:1], 0, s[6:7]
.LBB0_636:
	global_load_dwordx4 v[18:21], v[0:1], off
	global_load_dwordx4 v[22:25], v[0:1], off offset:-16
	v_add_u32_e32 v4, s62, v4
	v_max_f32_e32 v3, v3, v3
	v_cmp_lt_i32_e32 vcc, s64, v4
	s_or_b64 s[34:35], vcc, s[34:35]
	v_lshl_add_u64 v[0:1], v[0:1], 0, s[6:7]
	s_waitcnt vmcnt(2)
	v_lshlrev_b32_e32 v17, 16, v13
	v_lshlrev_b32_e32 v16, 16, v12
	v_and_b32_e32 v13, 0xffff0000, v13
	v_and_b32_e32 v12, 0xffff0000, v12
	v_pk_mul_f32 v[12:13], v[12:13], v[12:13]
	s_nop 0
	v_pk_fma_f32 v[12:13], v[16:17], v[16:17], v[12:13]
	v_lshlrev_b32_e32 v17, 16, v15
	v_lshlrev_b32_e32 v16, 16, v14
	v_and_b32_e32 v15, 0xffff0000, v15
	v_and_b32_e32 v14, 0xffff0000, v14
	v_pk_mul_f32 v[14:15], v[14:15], v[14:15]
	v_add_f32_e32 v12, v12, v13
	v_pk_fma_f32 v[14:15], v[16:17], v[16:17], v[14:15]
	v_lshlrev_b32_e32 v17, 16, v9
	v_lshlrev_b32_e32 v16, 16, v8
	v_and_b32_e32 v9, 0xffff0000, v9
	v_and_b32_e32 v8, 0xffff0000, v8
	v_pk_mul_f32 v[8:9], v[8:9], v[8:9]
	v_add_f32_e32 v12, v12, v14
	v_pk_fma_f32 v[8:9], v[16:17], v[16:17], v[8:9]
	v_lshlrev_b32_e32 v17, 16, v11
	v_lshlrev_b32_e32 v16, 16, v10
	v_and_b32_e32 v11, 0xffff0000, v11
	v_and_b32_e32 v10, 0xffff0000, v10
	v_add_f32_e32 v12, v12, v15
	v_pk_mul_f32 v[10:11], v[10:11], v[10:11]
	v_add_f32_e32 v8, v12, v8
	v_pk_fma_f32 v[10:11], v[16:17], v[16:17], v[10:11]
	v_add_f32_e32 v8, v8, v9
	v_add_f32_e32 v8, v8, v10
	v_add_f32_e32 v8, v8, v11
	ds_bpermute_b32 v9, v5, v8
	s_waitcnt lgkmcnt(0)
	v_add_f32_e32 v8, v8, v9
	ds_bpermute_b32 v9, v6, v8
	s_waitcnt lgkmcnt(0)
	v_add_f32_e32 v8, v8, v9
	ds_bpermute_b32 v9, v7, v8
	s_waitcnt lgkmcnt(0)
	v_add_f32_e32 v8, v8, v9
	v_max_f32_e32 v3, v3, v8
	s_andn2_b64 exec, exec, s[34:35]
	s_cbranch_execz .Lkmax_done
	global_load_dwordx4 v[8:11], v[0:1], off
	global_load_dwordx4 v[12:15], v[0:1], off offset:-16
	v_add_u32_e32 v4, s62, v4
	v_max_f32_e32 v3, v3, v3
	v_cmp_lt_i32_e32 vcc, s64, v4
	s_or_b64 s[34:35], vcc, s[34:35]
	v_lshl_add_u64 v[0:1], v[0:1], 0, s[6:7]
	s_waitcnt vmcnt(2)
	v_lshlrev_b32_e32 v17, 16, v23
	v_lshlrev_b32_e32 v16, 16, v22
	v_and_b32_e32 v23, 0xffff0000, v23
	v_and_b32_e32 v22, 0xffff0000, v22
	v_pk_mul_f32 v[22:23], v[22:23], v[22:23]
	s_nop 0
	v_pk_fma_f32 v[22:23], v[16:17], v[16:17], v[22:23]
	v_lshlrev_b32_e32 v17, 16, v25
	v_lshlrev_b32_e32 v16, 16, v24
	v_and_b32_e32 v25, 0xffff0000, v25
	v_and_b32_e32 v24, 0xffff0000, v24
	v_pk_mul_f32 v[24:25], v[24:25], v[24:25]
	v_add_f32_e32 v22, v22, v23
	v_pk_fma_f32 v[24:25], v[16:17], v[16:17], v[24:25]
	v_lshlrev_b32_e32 v17, 16, v19
	v_lshlrev_b32_e32 v16, 16, v18
	v_and_b32_e32 v19, 0xffff0000, v19
	v_and_b32_e32 v18, 0xffff0000, v18
	v_pk_mul_f32 v[18:19], v[18:19], v[18:19]
	v_add_f32_e32 v22, v22, v24
	v_pk_fma_f32 v[18:19], v[16:17], v[16:17], v[18:19]
	v_lshlrev_b32_e32 v17, 16, v21
	v_lshlrev_b32_e32 v16, 16, v20
	v_and_b32_e32 v21, 0xffff0000, v21
	v_and_b32_e32 v20, 0xffff0000, v20
	v_add_f32_e32 v22, v22, v25
	v_pk_mul_f32 v[20:21], v[20:21], v[20:21]
	v_add_f32_e32 v18, v22, v18
	v_pk_fma_f32 v[20:21], v[16:17], v[16:17], v[20:21]
	v_add_f32_e32 v18, v18, v19
	v_add_f32_e32 v18, v18, v20
	v_add_f32_e32 v18, v18, v21
	ds_bpermute_b32 v19, v5, v18
	s_waitcnt lgkmcnt(0)
	v_add_f32_e32 v18, v18, v19
	ds_bpermute_b32 v19, v6, v18
	s_waitcnt lgkmcnt(0)
	v_add_f32_e32 v18, v18, v19
	ds_bpermute_b32 v19, v7, v18
	s_waitcnt lgkmcnt(0)
	v_add_f32_e32 v18, v18, v19
	v_max_f32_e32 v3, v3, v18
	s_andn2_b64 exec, exec, s[34:35]
	s_cbranch_execnz .LBB0_636
.Lkmax_done:
	s_waitcnt vmcnt(0)
	s_or_b64 exec, exec, s[34:35]
